# cand E + P1 K/V epilogue: the 8 rsm values loaded together before the first store; later sites copy from registers (no vmcnt(0) store drains)
# baseline (speedup 1.0000x reference)
.LBB0_344:
	s_lshl_b32 s1, s4, 8
	s_add_i32 s30, s1, s53
	v_or_b32_e32 v154, s30, v167
	v_ashrrev_i32_e32 v155, 31, v154
	v_lshl_add_u64 v[156:157], v[154:155], 2, s[10:11]
	global_load_dword v136, v[156:157], off
	global_load_dword v240, v[156:157], off offset:64
	global_load_dword v241, v[156:157], off offset:128
	global_load_dword v242, v[156:157], off offset:192
	global_load_dword v243, v[156:157], off offset:512
	global_load_dword v244, v[156:157], off offset:576
	global_load_dword v245, v[156:157], off offset:640
	global_load_dword v246, v[156:157], off offset:704
	s_ashr_i32 s26, s0, 3
	s_and_b32 s17, s0, 3
	s_and_b32 s1, s0, 4
	s_bitcmp1_b32 s0, 2
	s_cselect_b64 s[28:29], -1, 0
	s_cmp_eq_u32 s1, 0
	s_mov_b32 s1, 0x4080000
	s_cselect_b32 s1, s1, 0x5080000
	s_add_u32 s1, s90, s1
	s_addc_u32 s19, s91, 0
	s_ashr_i32 s27, s26, 31
	s_lshl_b64 s[4:5], s[26:27], 23
	s_add_u32 s24, s1, s4
	s_addc_u32 s25, s19, s5
	s_and_b32 s19, s0, -8
	s_ashr_i32 s0, s30, 8
	s_add_i32 s0, s0, s19
	s_lshl_b32 s0, s0, 2
	s_or_b32 s0, s0, s17
	s_ashr_i32 s1, s0, 31
	s_lshl_b64 s[0:1], s[0:1], 17
	s_mov_b64 s[4:5], -1
	s_waitcnt vmcnt(0)
	v_fmamk_f32 v136, v136, 0x3a800000, v172
	v_cmp_gt_f32_e32 vcc, s63, v136
	v_mul_f32_e32 v152, 0x4b800000, v136
	s_nop 0
	v_cndmask_b32_e32 v136, v136, v152, vcc
	v_rsq_f32_e32 v136, v136
	s_nop 0
	v_mul_f32_e32 v152, 0x45800000, v136
	v_cndmask_b32_e32 v160, v136, v152, vcc
	v_lshlrev_b64 v[152:153], 12, v[154:155]
	v_lshl_add_u64 v[158:159], s[24:25], 0, v[152:153]
	v_lshl_add_u32 v152, s17, 8, v138
	v_bitop3_b32 v136, s30, v173, v167 bitop3:0xc8
	v_ashrrev_i32_e32 v153, 31, v152
	v_pk_mul_f32 v[126:127], v[126:127], v[160:161] op_sel_hi:[1,0]
	v_pk_mul_f32 v[124:125], v[124:125], v[160:161] op_sel_hi:[1,0]
	v_pk_mul_f32 v[122:123], v[122:123], v[160:161] op_sel_hi:[1,0]
	v_pk_mul_f32 v[120:121], v[120:121], v[160:161] op_sel_hi:[1,0]
	v_lshl_add_u64 v[162:163], v[152:153], 2, v[158:159]
	s_and_b64 vcc, exec, s[28:29]
	v_lshl_add_u64 v[158:159], v[140:141], 0, s[0:1]
	v_lshlrev_b32_e32 v136, 1, v136
	global_store_dwordx4 v[162:163], v[124:127], off
	global_store_dwordx4 v[162:163], v[120:123], off offset:16
	s_cbranch_vccz .LBB0_346
	v_lshl_add_u64 v[164:165], v[158:159], 0, v[136:137]
	v_cvt_pk_bf16_f32 v161, v124, v137
	global_store_short v[164:165], v161, off
	v_cvt_pk_bf16_f32 v161, v120, v137
	global_store_short v[164:165], v161, off offset:2048
	v_cvt_pk_bf16_f32 v161, v125, v137
	global_store_short v[164:165], v161, off offset:512
	v_cvt_pk_bf16_f32 v161, v121, v137
	global_store_short v[164:165], v161, off offset:2560
	v_cvt_pk_bf16_f32 v161, v126, v137
	global_store_short v[164:165], v161, off offset:1024
	v_cvt_pk_bf16_f32 v161, v122, v137
	global_store_short v[164:165], v161, off offset:3072
	v_cvt_pk_bf16_f32 v161, v127, v137
	global_store_short v[164:165], v161, off offset:1536
	v_cvt_pk_bf16_f32 v161, v123, v137
	global_store_short v[164:165], v161, off offset:3584
	s_mov_b64 s[4:5], 0

.LBB0_352:
	s_nop 1
	v_or_b32_e32 v116, 16, v154
	v_ashrrev_i32_e32 v117, 31, v116
	v_lshl_add_u64 v[112:113], v[116:117], 2, s[10:11]
	v_lshlrev_b64 v[114:115], 12, v[116:117]
	s_movk_i32 s0, 0xdf
	v_lshl_add_u64 v[114:115], s[24:25], 0, v[114:115]
	v_lshl_add_u64 v[114:115], v[152:153], 2, v[114:115]
	v_mov_b32_e32 v112, v240
	v_fmamk_f32 v112, v112, 0x3a800000, v172
	v_cmp_gt_f32_e32 vcc, s63, v112
	v_mul_f32_e32 v113, 0x4b800000, v112
	s_nop 0
	v_cndmask_b32_e32 v112, v112, v113, vcc
	v_rsq_f32_e32 v112, v112
	s_nop 0
	v_mul_f32_e32 v113, 0x45800000, v112
	v_cndmask_b32_e32 v112, v112, v113, vcc
	v_bitop3_b32 v113, v154, s0, 16 bitop3:0xc8
	v_pk_mul_f32 v[110:111], v[110:111], v[112:113] op_sel_hi:[1,0]
	v_pk_mul_f32 v[108:109], v[108:109], v[112:113] op_sel_hi:[1,0]
	v_pk_mul_f32 v[106:107], v[106:107], v[112:113] op_sel_hi:[1,0]
	v_pk_mul_f32 v[104:105], v[104:105], v[112:113] op_sel_hi:[1,0]
	s_mov_b64 s[0:1], -1
	s_and_b64 vcc, exec, s[4:5]
	v_lshlrev_b32_e32 v136, 1, v113
	global_store_dwordx4 v[114:115], v[108:111], off
	global_store_dwordx4 v[114:115], v[104:107], off offset:16
	s_cbranch_vccnz .LBB0_354
	v_lshl_add_u64 v[118:119], v[158:159], 0, v[136:137]
	v_cvt_pk_bf16_f32 v113, v108, v137
	global_store_short v[118:119], v113, off
	v_cvt_pk_bf16_f32 v113, v104, v137
	global_store_short v[118:119], v113, off offset:2048
	v_cvt_pk_bf16_f32 v113, v109, v137
	global_store_short v[118:119], v113, off offset:512
	v_cvt_pk_bf16_f32 v113, v105, v137
	global_store_short v[118:119], v113, off offset:2560
	v_cvt_pk_bf16_f32 v113, v110, v137
	global_store_short v[118:119], v113, off offset:1024
	v_cvt_pk_bf16_f32 v113, v106, v137
	global_store_short v[118:119], v113, off offset:3072
	v_cvt_pk_bf16_f32 v113, v111, v137
	s_mov_b64 s[0:1], 0
	global_store_short v[118:119], v113, off offset:1536
	v_cvt_pk_bf16_f32 v113, v107, v137
	global_store_short v[118:119], v113, off offset:3584

.LBB0_360:
	s_nop 1
	v_or_b32_e32 v100, 32, v154
	v_ashrrev_i32_e32 v101, 31, v100
	v_lshl_add_u64 v[96:97], v[100:101], 2, s[10:11]
	v_lshlrev_b64 v[98:99], 12, v[100:101]
	s_movk_i32 s0, 0xef
	v_lshl_add_u64 v[98:99], s[24:25], 0, v[98:99]
	v_lshl_add_u64 v[98:99], v[152:153], 2, v[98:99]
	v_mov_b32_e32 v96, v241
	v_fmamk_f32 v96, v96, 0x3a800000, v172
	v_cmp_gt_f32_e32 vcc, s63, v96
	v_mul_f32_e32 v97, 0x4b800000, v96
	s_nop 0
	v_cndmask_b32_e32 v96, v96, v97, vcc
	v_rsq_f32_e32 v96, v96
	s_nop 0
	v_mul_f32_e32 v97, 0x45800000, v96
	v_cndmask_b32_e32 v96, v96, v97, vcc
	v_bitop3_b32 v97, v154, s0, 32 bitop3:0xc8
	v_pk_mul_f32 v[94:95], v[94:95], v[96:97] op_sel_hi:[1,0]
	v_pk_mul_f32 v[92:93], v[92:93], v[96:97] op_sel_hi:[1,0]
	v_pk_mul_f32 v[90:91], v[90:91], v[96:97] op_sel_hi:[1,0]
	v_pk_mul_f32 v[88:89], v[88:89], v[96:97] op_sel_hi:[1,0]
	s_mov_b64 s[0:1], -1
	s_and_b64 vcc, exec, s[4:5]
	v_lshlrev_b32_e32 v136, 1, v97
	global_store_dwordx4 v[98:99], v[92:95], off
	global_store_dwordx4 v[98:99], v[88:91], off offset:16
	s_cbranch_vccnz .LBB0_362
	v_lshl_add_u64 v[102:103], v[158:159], 0, v[136:137]
	v_cvt_pk_bf16_f32 v97, v92, v137
	global_store_short v[102:103], v97, off
	v_cvt_pk_bf16_f32 v97, v88, v137
	global_store_short v[102:103], v97, off offset:2048
	v_cvt_pk_bf16_f32 v97, v93, v137
	global_store_short v[102:103], v97, off offset:512
	v_cvt_pk_bf16_f32 v97, v89, v137
	global_store_short v[102:103], v97, off offset:2560
	v_cvt_pk_bf16_f32 v97, v94, v137
	global_store_short v[102:103], v97, off offset:1024
	v_cvt_pk_bf16_f32 v97, v90, v137
	global_store_short v[102:103], v97, off offset:3072
	v_cvt_pk_bf16_f32 v97, v95, v137
	s_mov_b64 s[0:1], 0
	global_store_short v[102:103], v97, off offset:1536
	v_cvt_pk_bf16_f32 v97, v91, v137
	global_store_short v[102:103], v97, off offset:3584

.LBB0_368:
	s_nop 1
	v_or_b32_e32 v84, 48, v154
	v_ashrrev_i32_e32 v85, 31, v84
	v_lshl_add_u64 v[80:81], v[84:85], 2, s[10:11]
	v_lshlrev_b64 v[82:83], 12, v[84:85]
	s_movk_i32 s0, 0xff
	v_lshl_add_u64 v[82:83], s[24:25], 0, v[82:83]
	v_lshl_add_u64 v[82:83], v[152:153], 2, v[82:83]
	v_mov_b32_e32 v80, v242
	v_fmamk_f32 v80, v80, 0x3a800000, v172
	v_cmp_gt_f32_e32 vcc, s63, v80
	v_mul_f32_e32 v81, 0x4b800000, v80
	s_nop 0
	v_cndmask_b32_e32 v80, v80, v81, vcc
	v_rsq_f32_e32 v80, v80
	s_nop 0
	v_mul_f32_e32 v81, 0x45800000, v80
	v_cndmask_b32_e32 v80, v80, v81, vcc
	v_bitop3_b32 v81, v154, s0, 48 bitop3:0xc8
	v_pk_mul_f32 v[78:79], v[78:79], v[80:81] op_sel_hi:[1,0]
	v_pk_mul_f32 v[76:77], v[76:77], v[80:81] op_sel_hi:[1,0]
	v_pk_mul_f32 v[74:75], v[74:75], v[80:81] op_sel_hi:[1,0]
	v_pk_mul_f32 v[72:73], v[72:73], v[80:81] op_sel_hi:[1,0]
	s_mov_b64 s[0:1], -1
	s_and_b64 vcc, exec, s[4:5]
	v_lshlrev_b32_e32 v136, 1, v81
	global_store_dwordx4 v[82:83], v[76:79], off
	global_store_dwordx4 v[82:83], v[72:75], off offset:16
	s_cbranch_vccnz .LBB0_370
	v_lshl_add_u64 v[86:87], v[158:159], 0, v[136:137]
	v_cvt_pk_bf16_f32 v81, v76, v137
	global_store_short v[86:87], v81, off
	v_cvt_pk_bf16_f32 v81, v72, v137
	global_store_short v[86:87], v81, off offset:2048
	v_cvt_pk_bf16_f32 v81, v77, v137
	global_store_short v[86:87], v81, off offset:512
	v_cvt_pk_bf16_f32 v81, v73, v137
	global_store_short v[86:87], v81, off offset:2560
	v_cvt_pk_bf16_f32 v81, v78, v137
	global_store_short v[86:87], v81, off offset:1024
	v_cvt_pk_bf16_f32 v81, v74, v137
	global_store_short v[86:87], v81, off offset:3072
	v_cvt_pk_bf16_f32 v81, v79, v137
	s_mov_b64 s[0:1], 0
	global_store_short v[86:87], v81, off offset:1536
	v_cvt_pk_bf16_f32 v81, v75, v137
	global_store_short v[86:87], v81, off offset:3584

.LBB0_376:
	v_add_u32_e32 v66, 0x80, v154
	v_ashrrev_i32_e32 v64, 8, v66
	v_add_u32_e32 v68, s19, v64
	v_ashrrev_i32_e32 v67, 31, v66
	v_lshl_or_b32 v68, v68, 2, s17
	v_lshlrev_b64 v[64:65], 12, v[66:67]
	v_ashrrev_i32_e32 v69, 31, v68
	v_and_b32_e32 v73, 0xcf, v66
	v_lshl_add_u64 v[64:65], s[24:25], 0, v[64:65]
	v_lshlrev_b64 v[68:69], 17, v[68:69]
	s_mov_b64 s[28:29], -1
	s_and_b64 vcc, exec, s[4:5]
	v_lshlrev_b32_e32 v136, 1, v73
	v_mov_b32_e32 v70, v243
	v_fmamk_f32 v70, v70, 0x3a800000, v172
	v_mul_f32_e32 v71, 0x4b800000, v70
	v_cmp_gt_f32_e64 s[0:1], s63, v70
	s_nop 1
	v_cndmask_b32_e64 v70, v70, v71, s[0:1]
	v_rsq_f32_e32 v72, v70
	v_lshl_add_u64 v[70:71], v[152:153], 2, v[64:65]
	v_lshl_add_u64 v[64:65], v[140:141], 0, v[68:69]
	v_mul_f32_e32 v74, 0x45800000, v72
	v_cndmask_b32_e64 v72, v72, v74, s[0:1]
	v_pk_mul_f32 v[62:63], v[62:63], v[72:73] op_sel_hi:[1,0]
	v_pk_mul_f32 v[60:61], v[60:61], v[72:73] op_sel_hi:[1,0]
	v_pk_mul_f32 v[58:59], v[58:59], v[72:73] op_sel_hi:[1,0]
	v_pk_mul_f32 v[56:57], v[56:57], v[72:73] op_sel_hi:[1,0]
	global_store_dwordx4 v[70:71], v[60:63], off
	global_store_dwordx4 v[70:71], v[56:59], off offset:16
	s_cbranch_vccnz .LBB0_378
	v_lshl_add_u64 v[74:75], v[64:65], 0, v[136:137]
	v_cvt_pk_bf16_f32 v73, v60, v137
	global_store_short v[74:75], v73, off
	v_cvt_pk_bf16_f32 v73, v56, v137
	global_store_short v[74:75], v73, off offset:2048
	v_cvt_pk_bf16_f32 v73, v61, v137
	global_store_short v[74:75], v73, off offset:512
	v_cvt_pk_bf16_f32 v73, v57, v137
	global_store_short v[74:75], v73, off offset:2560
	v_cvt_pk_bf16_f32 v73, v62, v137
	global_store_short v[74:75], v73, off offset:1024
	v_cvt_pk_bf16_f32 v73, v58, v137
	global_store_short v[74:75], v73, off offset:3072
	v_cvt_pk_bf16_f32 v73, v63, v137
	s_mov_b64 s[28:29], 0
	global_store_short v[74:75], v73, off offset:1536
	v_cvt_pk_bf16_f32 v73, v59, v137
	global_store_short v[74:75], v73, off offset:3584

.LBB0_384:
	v_add_u32_e32 v48, 0x90, v154
	v_ashrrev_i32_e32 v49, 31, v48
	v_and_b32_e32 v53, 0xdf, v48
	s_mov_b64 s[28:29], -1
	s_and_b64 vcc, exec, s[4:5]
	v_lshlrev_b32_e32 v136, 1, v53
	v_mov_b32_e32 v50, v244
	v_fmamk_f32 v50, v50, 0x3a800000, v172
	v_mul_f32_e32 v51, 0x4b800000, v50
	v_cmp_gt_f32_e64 s[0:1], s63, v50
	s_nop 1
	v_cndmask_b32_e64 v50, v50, v51, s[0:1]
	v_rsq_f32_e32 v52, v50
	v_lshlrev_b64 v[50:51], 12, v[48:49]
	v_lshl_add_u64 v[50:51], s[24:25], 0, v[50:51]
	v_lshl_add_u64 v[50:51], v[152:153], 2, v[50:51]
	v_mul_f32_e32 v54, 0x45800000, v52
	v_cndmask_b32_e64 v52, v52, v54, s[0:1]
	v_pk_mul_f32 v[46:47], v[46:47], v[52:53] op_sel_hi:[1,0]
	v_pk_mul_f32 v[44:45], v[44:45], v[52:53] op_sel_hi:[1,0]
	v_pk_mul_f32 v[42:43], v[42:43], v[52:53] op_sel_hi:[1,0]
	v_pk_mul_f32 v[40:41], v[40:41], v[52:53] op_sel_hi:[1,0]
	global_store_dwordx4 v[50:51], v[44:47], off
	global_store_dwordx4 v[50:51], v[40:43], off offset:16
	s_cbranch_vccnz .LBB0_386
	v_lshl_add_u64 v[54:55], v[64:65], 0, v[136:137]
	v_cvt_pk_bf16_f32 v53, v44, v137
	global_store_short v[54:55], v53, off
	v_cvt_pk_bf16_f32 v53, v40, v137
	global_store_short v[54:55], v53, off offset:2048
	v_cvt_pk_bf16_f32 v53, v45, v137
	global_store_short v[54:55], v53, off offset:512
	v_cvt_pk_bf16_f32 v53, v41, v137
	global_store_short v[54:55], v53, off offset:2560
	v_cvt_pk_bf16_f32 v53, v46, v137
	global_store_short v[54:55], v53, off offset:1024
	v_cvt_pk_bf16_f32 v53, v42, v137
	global_store_short v[54:55], v53, off offset:3072
	v_cvt_pk_bf16_f32 v53, v47, v137
	s_mov_b64 s[28:29], 0
	global_store_short v[54:55], v53, off offset:1536
	v_cvt_pk_bf16_f32 v53, v43, v137
	global_store_short v[54:55], v53, off offset:3584

.LBB0_392:
	v_add_u32_e32 v32, 0xa0, v154
	v_ashrrev_i32_e32 v33, 31, v32
	v_and_b32_e32 v37, 0xef, v32
	s_mov_b64 s[28:29], -1
	s_and_b64 vcc, exec, s[4:5]
	v_lshlrev_b32_e32 v136, 1, v37
	v_mov_b32_e32 v34, v245
	v_fmamk_f32 v34, v34, 0x3a800000, v172
	v_mul_f32_e32 v35, 0x4b800000, v34
	v_cmp_gt_f32_e64 s[0:1], s63, v34
	s_nop 1
	v_cndmask_b32_e64 v34, v34, v35, s[0:1]
	v_rsq_f32_e32 v36, v34
	v_lshlrev_b64 v[34:35], 12, v[32:33]
	v_lshl_add_u64 v[34:35], s[24:25], 0, v[34:35]
	v_lshl_add_u64 v[34:35], v[152:153], 2, v[34:35]
	v_mul_f32_e32 v38, 0x45800000, v36
	v_cndmask_b32_e64 v36, v36, v38, s[0:1]
	v_pk_mul_f32 v[30:31], v[30:31], v[36:37] op_sel_hi:[1,0]
	v_pk_mul_f32 v[28:29], v[28:29], v[36:37] op_sel_hi:[1,0]
	v_pk_mul_f32 v[26:27], v[26:27], v[36:37] op_sel_hi:[1,0]
	v_pk_mul_f32 v[24:25], v[24:25], v[36:37] op_sel_hi:[1,0]
	global_store_dwordx4 v[34:35], v[28:31], off
	global_store_dwordx4 v[34:35], v[24:27], off offset:16
	s_cbranch_vccnz .LBB0_394
	v_lshl_add_u64 v[38:39], v[64:65], 0, v[136:137]
	v_cvt_pk_bf16_f32 v37, v28, v137
	global_store_short v[38:39], v37, off
	v_cvt_pk_bf16_f32 v37, v24, v137
	global_store_short v[38:39], v37, off offset:2048
	v_cvt_pk_bf16_f32 v37, v29, v137
	global_store_short v[38:39], v37, off offset:512
	v_cvt_pk_bf16_f32 v37, v25, v137
	global_store_short v[38:39], v37, off offset:2560
	v_cvt_pk_bf16_f32 v37, v30, v137
	global_store_short v[38:39], v37, off offset:1024
	v_cvt_pk_bf16_f32 v37, v26, v137
	global_store_short v[38:39], v37, off offset:3072
	v_cvt_pk_bf16_f32 v37, v31, v137
	s_mov_b64 s[28:29], 0
	global_store_short v[38:39], v37, off offset:1536
	v_cvt_pk_bf16_f32 v37, v27, v137
	global_store_short v[38:39], v37, off offset:3584

.LBB0_400:
	v_add_u32_e32 v16, 0xb0, v154
	v_ashrrev_i32_e32 v17, 31, v16
	s_mov_b64 s[28:29], -1
	s_and_b64 vcc, exec, s[4:5]
	v_lshlrev_b32_sdwa v136, v166, v16 dst_sel:DWORD dst_unused:UNUSED_PAD src0_sel:DWORD src1_sel:BYTE_0
	v_mov_b32_e32 v18, v246
	v_fmamk_f32 v18, v18, 0x3a800000, v172
	v_mul_f32_e32 v19, 0x4b800000, v18
	v_cmp_gt_f32_e64 s[0:1], s63, v18
	s_nop 1
	v_cndmask_b32_e64 v18, v18, v19, s[0:1]
	v_rsq_f32_e32 v20, v18
	v_lshlrev_b64 v[18:19], 12, v[16:17]
	v_lshl_add_u64 v[18:19], s[24:25], 0, v[18:19]
	v_lshl_add_u64 v[18:19], v[152:153], 2, v[18:19]
	v_mul_f32_e32 v21, 0x45800000, v20
	v_cndmask_b32_e64 v20, v20, v21, s[0:1]
	v_pk_mul_f32 v[14:15], v[14:15], v[20:21] op_sel_hi:[1,0]
	v_pk_mul_f32 v[12:13], v[12:13], v[20:21] op_sel_hi:[1,0]
	v_pk_mul_f32 v[10:11], v[10:11], v[20:21] op_sel_hi:[1,0]
	v_pk_mul_f32 v[8:9], v[8:9], v[20:21] op_sel_hi:[1,0]
	global_store_dwordx4 v[18:19], v[12:15], off
	global_store_dwordx4 v[18:19], v[8:11], off offset:16
	s_cbranch_vccnz .LBB0_402
	v_lshl_add_u64 v[22:23], v[64:65], 0, v[136:137]
	v_cvt_pk_bf16_f32 v21, v12, v137
	global_store_short v[22:23], v21, off
	v_cvt_pk_bf16_f32 v21, v8, v137
	global_store_short v[22:23], v21, off offset:2048
	v_cvt_pk_bf16_f32 v21, v13, v137
	global_store_short v[22:23], v21, off offset:512
	v_cvt_pk_bf16_f32 v21, v9, v137
	global_store_short v[22:23], v21, off offset:2560
	v_cvt_pk_bf16_f32 v21, v14, v137
	global_store_short v[22:23], v21, off offset:1024
	v_cvt_pk_bf16_f32 v21, v10, v137
	global_store_short v[22:23], v21, off offset:3072
	v_cvt_pk_bf16_f32 v21, v15, v137
	s_mov_b64 s[28:29], 0
	global_store_short v[22:23], v21, off offset:1536
	v_cvt_pk_bf16_f32 v21, v11, v137
	global_store_short v[22:23], v21, off offset:3584
